# back-edge rotation of the attention kv-tile loop: exit test and loop-carried copy moved ahead of the loop-back barrier, which becomes the loop head
# baseline (speedup 1.0000x reference)
; #define SBAR() __builtin_amdgcn_sched_barrier(0)
; __device__ __forceinline__ int v_st(int k, int c) { const int kk = (k & ~0xC) | ((k & 4) << 1) | ((k & 8) >> 1); return ((kk >> 3) * 4 + (c >> 5)) * 512 + ((kk & 7) * 32 + (c & 31)) * 2; }
; __device__ __forceinline__ int v_rd_base(int lane) { return ((lane & 3) << 3) | (((lane >> 2) & 3) << 6) | (((lane >> 4) & 1) << 5) | (((lane >> 5) & 1) << 8); }
; #define VMW() asm volatile("s_waitcnt vmcnt(0)" ::: "memory")
; #define SWRITE_HV(bf) do { *(bf16x8*)(V_lds + (bf) * SHM_V + vst0) = S.st_v0; *(bf16x8*)(V_lds + (bf) * SHM_V + vst1) = S.st_v1; } while (0)
; #define SWRITE_H(bf) do { SWRITE_HV(bf); SWRITE_HK(bf); } while (0)
; #define SWRITE_KF(bf) do { *(bf16x8*)(K_lds + (bf) * SHM_K + kws) = pack8(S.sf0, S.sf1); *(bf16x8*)(K_lds + (bf) * SHM_K + kws + 32 * 256) = pack8(S.sf2, S.sf3); } while (0)
; template <class TIn, class TOut, bool NB = false>
; __device__ __forceinline__ void causal_swa_block(const BlockRef<TIn, TOut>& cur, const BlockRef<TIn, TOut>& nxt, int skv, int W, char* lds, Seam<TIn>& S) {
;     ...
;     float* ws = (float*)(lds + 2 * SHM_V + 2 * SHM_K) + wid * 64; float* li_l = ws, * al_l = ws + 32;
;     float m_reg = -1e30f, l_reg = 0; f32x16 o[4] = {};
;     const int sr = tid >> 4, sc = (tid & 15) * 8, vst0 = v_st(sr, sc), vst1 = v_st(32 + sr, sc), kws = KSWZ(sr, sc * 2);
;     const int vb0 = (int)(uintptr_t)V_lds + v_rd_base(lane);
;     const TIn* Kh = cur.K; const TIn* Vh = cur.V; const float* Gh = cur.G; const float* g_lds = (const float*)(K_lds + 2 * SHM_K + NW * 256);
;     ...
;     constexpr int NQL = F32 ? 16 : 8;
;     constexpr bool SK = WSKIP && !F32;
;     ...
;     f32x16 pA0, pA1, pB0, pB1; float mnA, mnB, alA, alB; bf16x8 pa0, pa1, pa2, pa3;
;     if constexpr (F32) { VMW(); SWRITE_VF(0); SBAR(); } else { SWRITE_HV(0); SBAR(); }
;     if (NT > 1) { if constexpr (F32) SLOAD_F((const float*)Kh, KBASE(1)); else SLOAD_H(Kh, Vh, Gh, KBASE(1)); }
;     SBAR(); qkt<0, SK, NB>(pA0, pA1, K_lds, r32, hi, S.qr, ACT(0), g_lds, S.gt);
;     if constexpr (F32) { if (NT > 1) { VMW(); SWRITE_KF(1); SBAR(); SLOAD_F((const float*)Vh, KBASE(1)); } }
;     MASKT(pA0, pA1, 0); partialSM(pA0, pA1, m_reg, mnA, alA);
;     if (NT > 1) { VMW(); if constexpr (F32) { SWRITE_VF(1); SBAR(); if (NT > 2) SLOAD_F((const float*)Kh, KBASE(2)); } else SWRITE_H(1); }
;     __syncthreads();
.LBB0_802:
	v_max_f32_e32 v41, 0xf149f2ca, v52
	v_cndmask_b32_e64 v176, v41, v204, s[8:9]
	v_mul_f32_e32 v40, 0xbe0293ee, v176
	v_fmamk_f32 v16, v16, 0x3e0293ee, v40
	v_exp_f32_e32 v173, v16
	v_sub_f32_e32 v16, 0xf149f2ca, v41
	v_mul_f32_e32 v16, 0x3e0293ee, v16
	v_exp_f32_e32 v16, v16
	v_pk_fma_f32 v[122:123], v[2:3], s[16:17], v[40:41] op_sel_hi:[1,0,0]
	v_pk_fma_f32 v[124:125], v[0:1], s[16:17], v[40:41] op_sel_hi:[1,0,0]
	v_lshlrev_b32_e32 v0, 8, v48
	v_cndmask_b32_e64 v223, v16, 1.0, s[8:9]
	s_and_b32 s8, s49, 0x3fffffc0
	s_lshl_b32 s8, s8, 2
	s_add_i32 s8, s8, 0
	s_add_i32 s46, s8, 0x10000
	v_and_b32_e32 v1, 0x70, v206
	v_lshlrev_b32_e32 v2, 4, v51
	v_bitop3_b32 v0, v49, v0, v1 bitop3:0xde
	v_lshlrev_b32_e32 v1, 3, v51
	v_and_b32_e32 v2, 0xc0, v2
	v_lshlrev_b32_e32 v3, 1, v51
	s_cmp_lg_u32 0, -1
	v_mov_b32_e32 v197, v195
	v_fmamk_f32 v17, v17, 0x3e0293ee, v40
	v_fmamk_f32 v18, v18, 0x3e0293ee, v40
	v_fmamk_f32 v19, v19, 0x3e0293ee, v40
	v_fmamk_f32 v20, v20, 0x3e0293ee, v40
	v_fmamk_f32 v21, v21, 0x3e0293ee, v40
	v_fmamk_f32 v22, v22, 0x3e0293ee, v40
	v_fmamk_f32 v23, v23, 0x3e0293ee, v40
	v_fmamk_f32 v24, v24, 0x3e0293ee, v40
	v_fmamk_f32 v25, v25, 0x3e0293ee, v40
	v_fmamk_f32 v26, v26, 0x3e0293ee, v40
	v_fmamk_f32 v27, v27, 0x3e0293ee, v40
	v_fmamk_f32 v28, v28, 0x3e0293ee, v40
	v_fmamk_f32 v29, v29, 0x3e0293ee, v40
	v_fmamk_f32 v30, v30, 0x3e0293ee, v40
	v_fmamk_f32 v31, v31, 0x3e0293ee, v40
	v_and_or_b32 v2, v1, 24, v2
	v_and_b32_e32 v3, 32, v3
	v_and_b32_e32 v1, 0x100, v1
	s_cselect_b32 s8, 0, 0
	v_lshl_add_u64 v[200:201], s[10:11], 0, v[196:197]
	s_add_i32 s10, s31, 0xc0
	v_exp_f32_e32 v175, v17
	v_exp_f32_e32 v171, v18
	v_exp_f32_e32 v174, v19
	v_exp_f32_e32 v170, v20
	v_exp_f32_e32 v172, v21
	v_exp_f32_e32 v168, v22
	v_exp_f32_e32 v169, v23
	v_exp_f32_e32 v163, v24
	v_exp_f32_e32 v166, v25
	v_exp_f32_e32 v161, v26
	v_exp_f32_e32 v164, v27
	v_exp_f32_e32 v160, v28
	v_exp_f32_e32 v167, v29
	v_exp_f32_e32 v162, v30
	v_exp_f32_e32 v165, v31
	v_or3_b32 v1, v2, v3, v1
	v_add_u32_e32 v210, 0, v0
	v_add_u32_e32 v0, s10, v208
	v_add_u32_e32 v213, s8, v1
	ds_write_b128 v210, v[32:35] offset:49152
	ds_write_b128 v210, v[36:39] offset:57344
	s_add_i32 s8, 0, 0x10800
	v_sub_u32_e32 v0, v0, v50
	v_mov_b32_e32 v32, v195
	v_mov_b32_e32 v33, v195
	v_mov_b32_e32 v46, v195
	v_mov_b32_e32 v47, v195
	v_pk_fma_f32 v[116:117], v[14:15], s[16:17], v[40:41] op_sel_hi:[1,0,0]
	v_pk_fma_f32 v[120:121], v[12:13], s[16:17], v[40:41] op_sel_hi:[1,0,0]
	v_pk_fma_f32 v[126:127], v[10:11], s[16:17], v[40:41] op_sel_hi:[1,0,0]
	v_pk_fma_f32 v[112:113], v[8:9], s[16:17], v[40:41] op_sel_hi:[1,0,0]
	v_pk_fma_f32 v[114:115], v[6:7], s[16:17], v[40:41] op_sel_hi:[1,0,0]
	v_pk_fma_f32 v[118:119], v[4:5], s[16:17], v[40:41] op_sel_hi:[1,0,0]
	v_lshl_add_u32 v212, v51, 2, s8
	v_cmp_gt_u32_e64 s[8:9], 32, v51
	v_lshl_add_u32 v209, v50, 2, s46
	v_subrev_u32_e32 v224, s48, v0
	v_mov_b32_e32 v34, v195
	v_mov_b32_e32 v35, v195
	v_mov_b32_e32 v36, v195
	v_mov_b32_e32 v37, v195
	v_mov_b32_e32 v38, v195
	v_mov_b32_e32 v39, v195
	v_mov_b32_e32 v40, v195
	v_mov_b32_e32 v41, v195
	v_mov_b32_e32 v42, v195
	v_mov_b32_e32 v43, v195
	v_mov_b32_e32 v44, v195
	v_mov_b32_e32 v45, v195
	v_mov_b64_e32 v[62:63], v[46:47]
	v_mov_b64_e32 v[16:17], v[32:33]
	v_mov_b64_e32 v[0:1], v[32:33]
	s_mov_b32 s68, 2
	v_lshl_add_u32 v211, v208, 2, s46
	v_mov_b32_e32 v222, 0
	v_mov_b64_e32 v[60:61], v[44:45]
	v_mov_b64_e32 v[58:59], v[42:43]
	v_mov_b64_e32 v[56:57], v[40:41]
	v_mov_b64_e32 v[54:55], v[38:39]
	v_mov_b64_e32 v[52:53], v[36:37]
	v_mov_b64_e32 v[50:51], v[34:35]
	v_mov_b64_e32 v[48:49], v[32:33]
	v_mov_b64_e32 v[18:19], v[34:35]
	v_mov_b64_e32 v[20:21], v[36:37]
	v_mov_b64_e32 v[22:23], v[38:39]
	v_mov_b64_e32 v[24:25], v[40:41]
	v_mov_b64_e32 v[26:27], v[42:43]
	v_mov_b64_e32 v[28:29], v[44:45]
	v_mov_b64_e32 v[30:31], v[46:47]
	v_mov_b64_e32 v[2:3], v[34:35]
	v_mov_b64_e32 v[4:5], v[36:37]
	v_mov_b64_e32 v[6:7], v[38:39]
	v_mov_b64_e32 v[8:9], v[40:41]
	v_mov_b64_e32 v[10:11], v[42:43]
	v_mov_b64_e32 v[12:13], v[44:45]
	v_mov_b64_e32 v[14:15], v[46:47]
	s_waitcnt lgkmcnt(0)
.Lattn_head:
	s_barrier
;     __device__ __forceinline__ static float act(float g, float u) { return g * __builtin_amdgcn_rcpf(1.0f + __builtin_amdgcn_exp2f(g * -1.4426950408889634f)) * u; }
; __device__ __forceinline__ void finishSM(f32x16& p0, f32x16& p1, float alpha, float& l_reg, bf16x8& pa0, bf16x8& pa1, bf16x8& pa2, bf16x8& pa3) {
;     for (int r = 0; r < 16; ++r) p1[r] = __builtin_amdgcn_exp2f(p1[r]);
;     float ps = 0; for (int r = 0; r < 16; ++r) ps += p0[r]; for (int r = 0; r < 16; ++r) ps += p1[r];
;     { auto rr = __builtin_amdgcn_permlane32_swap(__float_as_uint(ps), __float_as_uint(ps), false, false);
;       ps = __uint_as_float(rr[0]) + __uint_as_float(rr[1]); }
;     l_reg = l_reg * alpha + ps;
;     ...
;     PK4(p0, 0, pa0); PK4(p0, 8, pa1); PK4(p1, 0, pa2); PK4(p1, 8, pa3);
; template <int KB, bool SK, bool NB = false>
; __device__ __forceinline__ void qkt(f32x16& p0, f32x16& p1, const char* K_lds, int r32, int hi, const bf16x8* qr, bool act, const float* g_lds, float gt) {
;     if (SK && !act) { const float NEG = -__builtin_inff();
; #pragma unroll
;         for (int r = 0; r < 16; ++r) { p0[r] = NEG; p1[r] = NEG; } return; }
;     if constexpr (NB) { p0 = f32x16{}; p1 = f32x16{}; } else
;     { const float* gl = g_lds + KB * 64 + 4 * hi;
; #pragma unroll
;       for (int g4 = 0; g4 < 4; ++g4) { const f32x4 a = *(const f32x4*)(gl + 8 * g4), b = *(const f32x4*)(gl + 32 + 8 * g4);
; #pragma unroll
;         for (int e = 0; e < 4; ++e) { p0[4 * g4 + e] = a[e]; p1[4 * g4 + e] = b[e]; } } }
;     const char* kb[4];
; #pragma unroll
;     for (int dd = 0; dd < 4; ++dd) kb[dd] = K_lds + KB * SHM_K + KSWZ(r32, (dd * 16 + hi * 8) * 2);
; #pragma unroll
;     for (int d0 = 0; d0 < 8; ++d0) { const char* a = kb[d0 & 3] + (d0 >> 2) * 128;
;         bf16x8 b0 = *reinterpret_cast<const bf16x8*>(a);
;         bf16x8 b1 = *reinterpret_cast<const bf16x8*>(a + 32 * 256);
;         p0 = __builtin_amdgcn_mfma_f32_32x32x16_bf16(b0, qr[d0], p0, 0, 0, 0);
;         p1 = __builtin_amdgcn_mfma_f32_32x32x16_bf16(b1, qr[d0], p1, 0, 0, 0); }
.LBB0_803:
	v_add_u32_e32 v225, 0x10900, v218
	ds_read_b128 v[64:67], v216 offset:49152
	ds_read_b128 v[84:87], v225
	ds_read_b128 v[88:91], v225 offset:32
	ds_read_b128 v[92:95], v225 offset:64
	ds_read_b128 v[96:99], v225 offset:96
	ds_read_b128 v[100:103], v216 offset:57344
	ds_read_b128 v[104:107], v216 offset:49280
	v_add_f32_e32 v177, 0, v173
	s_waitcnt lgkmcnt(2)
	v_mfma_f32_32x32x16_bf16 v[84:99], v[64:67], v[156:159], v[84:99]
	ds_read_b128 v[68:71], v225 offset:128
	ds_read_b128 v[72:75], v225 offset:160
	ds_read_b128 v[76:79], v225 offset:192
	ds_read_b128 v[80:83], v225 offset:224
	ds_read_b128 v[64:67], v216 offset:57472
	v_add_f32_e32 v177, v175, v177
	v_add_f32_e32 v177, v171, v177
	v_add_f32_e32 v177, v174, v177
	v_add_f32_e32 v177, v170, v177
	v_add_f32_e32 v177, v172, v177
	v_add_f32_e32 v177, v168, v177
	s_waitcnt lgkmcnt(1)
	v_mfma_f32_32x32x16_bf16 v[68:83], v[100:103], v[156:159], v[68:83]
	ds_read_b128 v[100:103], v217 offset:49152
	ds_read_b128 v[108:111], v217 offset:57344
	ds_read_b128 v[178:181], v217 offset:49280
	v_add_f32_e32 v177, v169, v177
	v_add_f32_e32 v177, v163, v177
	v_add_f32_e32 v177, v166, v177
	v_exp_f32_e32 v124, v124
	v_exp_f32_e32 v125, v125
	v_exp_f32_e32 v122, v122
	s_waitcnt lgkmcnt(2)
	v_mfma_f32_32x32x16_bf16 v[84:99], v[100:103], v[152:155], v[84:99]
	ds_read_b128 v[100:103], v217 offset:57472
	ds_read_b128 v[182:185], v220 offset:49152
	ds_read_b128 v[186:189], v220 offset:49280
	ds_read_b128 v[226:229], v220 offset:57344
	ds_read_b128 v[230:233], v220 offset:57472
	ds_read_b128 v[234:237], v221 offset:49152
	ds_read_b128 v[238:241], v221 offset:49280
	v_exp_f32_e32 v123, v123
	v_exp_f32_e32 v118, v118
	v_exp_f32_e32 v119, v119
	v_exp_f32_e32 v114, v114
	v_exp_f32_e32 v115, v115
	v_exp_f32_e32 v112, v112
	s_waitcnt lgkmcnt(8)
	v_mfma_f32_32x32x16_bf16 v[68:83], v[108:111], v[152:155], v[68:83]
	ds_read_b128 v[108:111], v221 offset:57344
	ds_read_b128 v[242:245], v221 offset:57472
	v_exp_f32_e32 v113, v113
	v_exp_f32_e32 v126, v126
	v_exp_f32_e32 v127, v127
	v_exp_f32_e32 v120, v120
	v_exp_f32_e32 v121, v121
	v_exp_f32_e32 v116, v116
	s_waitcnt lgkmcnt(7)
	v_mfma_f32_32x32x16_bf16 v[84:99], v[182:185], v[148:151], v[84:99]
	v_exp_f32_e32 v117, v117
	s_waitcnt lgkmcnt(5)
	v_mfma_f32_32x32x16_bf16 v[68:83], v[226:229], v[148:151], v[68:83]
	s_waitcnt lgkmcnt(3)
	v_mfma_f32_32x32x16_bf16 v[84:99], v[234:237], v[144:147], v[84:99]
	s_waitcnt lgkmcnt(1)
	v_mfma_f32_32x32x16_bf16 v[68:83], v[108:111], v[144:147], v[68:83]
	v_add_f32_e32 v108, v161, v177
	v_add_f32_e32 v108, v164, v108
	v_add_f32_e32 v108, v160, v108
	v_add_f32_e32 v108, v167, v108
	v_add_f32_e32 v108, v162, v108
	v_add_f32_e32 v108, v165, v108
	v_add_f32_e32 v108, v124, v108
	v_mfma_f32_32x32x16_bf16 v[84:99], v[104:107], v[140:143], v[84:99]
	v_add_f32_e32 v104, v125, v108
	v_add_f32_e32 v104, v122, v104
	v_add_f32_e32 v104, v123, v104
	v_add_f32_e32 v104, v118, v104
	v_add_f32_e32 v104, v119, v104
	v_add_f32_e32 v104, v114, v104
	v_add_f32_e32 v104, v115, v104
	v_mfma_f32_32x32x16_bf16 v[68:83], v[64:67], v[140:143], v[68:83]
	v_add_f32_e32 v64, v112, v104
	v_add_f32_e32 v64, v113, v64
	v_add_f32_e32 v64, v126, v64
	v_add_f32_e32 v64, v127, v64
	v_add_f32_e32 v64, v120, v64
	v_add_f32_e32 v64, v121, v64
	v_add_f32_e32 v64, v116, v64
	v_mfma_f32_32x32x16_bf16 v[84:99], v[178:181], v[136:139], v[84:99]
	v_add_f32_e32 v226, v117, v64
	v_mov_b32_e32 v227, v226
	v_cvt_pk_bf16_f32 v64, v173, v175
	v_cvt_pk_bf16_f32 v65, v171, v174
	v_cvt_pk_bf16_f32 v66, v170, v172
	v_cvt_pk_bf16_f32 v67, v168, v169
	s_nop 1
	v_permlane32_swap_b32_e32 v226, v227
	v_mfma_f32_32x32x16_bf16 v[68:83], v[100:103], v[136:139], v[68:83]
	v_cvt_pk_bf16_f32 v100, v163, v166
	v_cvt_pk_bf16_f32 v101, v161, v164
	v_cvt_pk_bf16_f32 v102, v160, v167
	v_cvt_pk_bf16_f32 v103, v162, v165
	v_cvt_pk_bf16_f32 v108, v124, v125
	v_cvt_pk_bf16_f32 v109, v122, v123
	v_cvt_pk_bf16_f32 v110, v118, v119
	v_mfma_f32_32x32x16_bf16 v[84:99], v[186:189], v[132:135], v[84:99]
	v_cvt_pk_bf16_f32 v111, v114, v115
	v_cvt_pk_bf16_f32 v104, v112, v113
	v_cvt_pk_bf16_f32 v105, v126, v127
	v_cvt_pk_bf16_f32 v106, v120, v121
	v_cvt_pk_bf16_f32 v107, v116, v117
	v_permlane32_swap_b32_e32 v64, v66
	v_mfma_f32_32x32x16_bf16 v[68:83], v[230:233], v[132:135], v[68:83]
	v_permlane32_swap_b32_e32 v65, v67
	v_permlane32_swap_b32_e32 v100, v102
	v_permlane32_swap_b32_e32 v101, v103
	v_permlane32_swap_b32_e32 v108, v110
	v_mfma_f32_32x32x16_bf16 v[84:99], v[238:241], v[128:131], v[84:99]
	v_permlane32_swap_b32_e32 v109, v111
	v_permlane32_swap_b32_e32 v104, v106
	v_permlane32_swap_b32_e32 v105, v107
	s_waitcnt lgkmcnt(0)
	v_mfma_f32_32x32x16_bf16 v[68:83], v[242:245], v[128:131], v[68:83]
	s_sub_i32 s46, s14, 64
	s_and_b64 vcc, exec, s[6:7]
	s_ashr_i32 s47, s46, 31
	s_cbranch_vccnz .LBB0_805
	v_lshl_add_u64 v[112:113], s[46:47], 2, v[200:201]
	flat_load_dword v202, v[112:113]

; #define SBAR() __builtin_amdgcn_sched_barrier(0)
; #define ACT(t) (KBASE(t) <= qlo + QBLK - 1 && KBASE(t) + KVBLK - 1 >= qlo - W + 1)
; __device__ __forceinline__ void partialSM(f32x16& p0, f32x16& p1, float& m_reg, float& mn, float& alpha) {
;     float pmax = p0[0]; for (int r = 1; r < 16; ++r) pmax = fmaxf(pmax, p0[r]); for (int r = 0; r < 16; ++r) pmax = fmaxf(pmax, p1[r]);
;     { auto rr = __builtin_amdgcn_permlane32_swap(__float_as_uint(pmax), __float_as_uint(pmax), false, false);
;       pmax = fmaxf(__uint_as_float(rr[0]), __uint_as_float(rr[1])); }
;     constexpr float C2 = 1.4426950408889634f * SCALE;
;     if (__builtin_expect(__all((pmax - m_reg) * SCALE <= THR), 1)) { mn = m_reg; alpha = 1.f; }
;     else { mn = fmaxf(m_reg, pmax); alpha = __builtin_amdgcn_exp2f((m_reg - mn) * C2); m_reg = mn; }
;     const float mnL = -mn * C2;
;     for (int r = 0; r < 16; ++r) p0[r] = fmaf(p0[r], C2, mnL); for (int r = 0; r < 16; ++r) p1[r] = fmaf(p1[r], C2, mnL);
;     for (int r = 0; r < 16; ++r) p0[r] = __builtin_amdgcn_exp2f(p0[r]);
; }
; __device__ __forceinline__ void finishSM(f32x16& p0, f32x16& p1, float alpha, float& l_reg, bf16x8& pa0, bf16x8& pa1, bf16x8& pa2, bf16x8& pa3) {
;     for (int r = 0; r < 16; ++r) p1[r] = __builtin_amdgcn_exp2f(p1[r]);
;     float ps = 0; for (int r = 0; r < 16; ++r) ps += p0[r]; for (int r = 0; r < 16; ++r) ps += p1[r];
;     { auto rr = __builtin_amdgcn_permlane32_swap(__float_as_uint(ps), __float_as_uint(ps), false, false);
;       ps = __uint_as_float(rr[0]) + __uint_as_float(rr[1]); }
;     l_reg = l_reg * alpha + ps;
; template <class TIn, class TOut, bool NB = false>
; __device__ __forceinline__ void causal_swa_block(const BlockRef<TIn, TOut>& cur, const BlockRef<TIn, TOut>& nxt, int skv, int W, char* lds, Seam<TIn>& S) {
;     ...
;     for (int t = 1; t + 1 < NT; t += 2) {
;         HALF_STEP(pB0, pB1, mnB, alB, pA0, pA1, alA, t, 1, 0, 0);
;         HALF_STEP(pA0, pA1, mnA, alA, pB0, pB1, alB, t + 1, 0, 1, 1);
;     }
;     const bool even = (NT & 1) == 0;
;     if (even) { SBAR(); qkt<1, SK, NB>(pB0, pB1, K_lds, r32, hi, S.qr, ACT(NT - 1), g_lds, S.gt); SBAR(); }
.LBB0_827:
	v_cndmask_b32_e64 v176, v160, v229, s[10:11]
	v_mul_f32_e32 v178, 0xbe0293ee, v176
	v_mov_b32_e32 v182, v178
	v_fmamk_f32 v160, v112, 0x3e0293ee, v178
	v_fmamk_f32 v161, v113, 0x3e0293ee, v178
	v_fmamk_f32 v162, v114, 0x3e0293ee, v178
	v_fmamk_f32 v163, v115, 0x3e0293ee, v178
	v_fmamk_f32 v116, v116, 0x3e0293ee, v178
	v_fmamk_f32 v117, v117, 0x3e0293ee, v178
	v_fmamk_f32 v164, v118, 0x3e0293ee, v178
	v_fmamk_f32 v165, v119, 0x3e0293ee, v178
	v_fmamk_f32 v120, v120, 0x3e0293ee, v178
	v_fmamk_f32 v121, v121, 0x3e0293ee, v178
	v_fmamk_f32 v167, v122, 0x3e0293ee, v178
	v_fmamk_f32 v179, v123, 0x3e0293ee, v178
	v_fmamk_f32 v180, v124, 0x3e0293ee, v178
	v_fmamk_f32 v181, v125, 0x3e0293ee, v178
	v_fmamk_f32 v126, v126, 0x3e0293ee, v178
	v_fmac_f32_e32 v182, 0x3e0293ee, v127
	v_exp_f32_e32 v173, v160
	v_exp_f32_e32 v175, v161
	v_exp_f32_e32 v171, v162
	v_exp_f32_e32 v174, v163
	v_exp_f32_e32 v170, v116
	v_exp_f32_e32 v172, v117
	v_exp_f32_e32 v168, v164
	v_exp_f32_e32 v169, v165
	v_exp_f32_e32 v163, v120
	v_exp_f32_e32 v166, v121
	v_exp_f32_e32 v161, v167
	v_exp_f32_e32 v164, v179
	v_exp_f32_e32 v160, v180
	v_exp_f32_e32 v167, v181
	v_exp_f32_e32 v162, v126
	v_exp_f32_e32 v165, v182
	v_pk_fma_f32 v[124:125], v[96:97], s[16:17], v[178:179] op_sel_hi:[1,0,0]
	v_add_f32_e32 v96, v226, v227
	v_fmac_f32_e32 v96, v223, v222
	v_add_f32_e32 v222, v230, v231
	s_addk_i32 s14, 0xff80
	s_add_i32 s68, s68, 2
	v_pk_fma_f32 v[122:123], v[98:99], s[16:17], v[178:179] op_sel_hi:[1,0,0]
	v_pk_fma_f32 v[118:119], v[100:101], s[16:17], v[178:179] op_sel_hi:[1,0,0]
	v_pk_fma_f32 v[114:115], v[102:103], s[16:17], v[178:179] op_sel_hi:[1,0,0]
	v_pk_fma_f32 v[112:113], v[104:105], s[16:17], v[178:179] op_sel_hi:[1,0,0]
	v_pk_fma_f32 v[126:127], v[106:107], s[16:17], v[178:179] op_sel_hi:[1,0,0]
	v_pk_fma_f32 v[120:121], v[108:109], s[16:17], v[178:179] op_sel_hi:[1,0,0]
	v_pk_fma_f32 v[116:117], v[110:111], s[16:17], v[178:179] op_sel_hi:[1,0,0]
	v_fmac_f32_e32 v222, v96, v228
	s_cmp_ge_u32 s68, s66
	v_add_u32_e32 v224, 0x80, v224
	s_waitcnt lgkmcnt(0)
	s_cbranch_scc1 .Lattn_exit
	v_mov_b32_e32 v223, v177
	s_branch .Lattn_head
.Lattn_exit:
	s_barrier
.LBB0_829:
	s_bitcmp0_b32 s66, 0
	s_cselect_b64 s[10:11], -1, 0
	s_and_b64 vcc, exec, s[10:11]
	s_cbranch_vccz .LBB0_831
	ds_read_b128 v[80:83], v216 offset:49152
	ds_read_b128 v[64:67], v225
	ds_read_b128 v[68:71], v225 offset:32
	ds_read_b128 v[72:75], v225 offset:64
	ds_read_b128 v[76:79], v225 offset:96
	ds_read_b128 v[96:99], v216 offset:57344
	ds_read_b128 v[100:103], v216 offset:49280
	s_waitcnt lgkmcnt(2)
	v_mfma_f32_32x32x16_bf16 v[64:79], v[80:83], v[156:159], v[64:79]
	ds_read_b128 v[80:83], v225 offset:128
	ds_read_b128 v[84:87], v225 offset:160
	ds_read_b128 v[88:91], v225 offset:192
	ds_read_b128 v[92:95], v225 offset:224
	ds_read_b128 v[104:107], v216 offset:57472
	s_waitcnt lgkmcnt(1)
	v_mfma_f32_32x32x16_bf16 v[80:95], v[96:99], v[156:159], v[80:95]
	ds_read_b128 v[96:99], v217 offset:49152
	ds_read_b128 v[108:111], v217 offset:49280
	s_waitcnt lgkmcnt(1)
	v_mfma_f32_32x32x16_bf16 v[64:79], v[96:99], v[152:155], v[64:79]
	ds_read_b128 v[96:99], v217 offset:57344
	ds_read_b128 v[156:159], v217 offset:57472
	s_waitcnt lgkmcnt(1)
	v_mfma_f32_32x32x16_bf16 v[80:95], v[96:99], v[152:155], v[80:95]
	ds_read_b128 v[96:99], v220 offset:49152
	ds_read_b128 v[152:155], v220 offset:49280
	s_waitcnt lgkmcnt(1)
	v_mfma_f32_32x32x16_bf16 v[64:79], v[96:99], v[148:151], v[64:79]
	ds_read_b128 v[96:99], v220 offset:57344
	ds_read_b128 v[178:181], v220 offset:57472
	s_waitcnt lgkmcnt(1)
	v_mfma_f32_32x32x16_bf16 v[80:95], v[96:99], v[148:151], v[80:95]
	ds_read_b128 v[96:99], v221 offset:49152
	ds_read_b128 v[148:151], v221 offset:49280
	s_waitcnt lgkmcnt(1)
	v_mfma_f32_32x32x16_bf16 v[64:79], v[96:99], v[144:147], v[64:79]
	ds_read_b128 v[96:99], v221 offset:57344
	ds_read_b128 v[182:185], v221 offset:57472
	s_waitcnt lgkmcnt(1)
	v_mfma_f32_32x32x16_bf16 v[80:95], v[96:99], v[144:147], v[80:95]
	v_mfma_f32_32x32x16_bf16 v[64:79], v[100:103], v[140:143], v[64:79]
	v_mfma_f32_32x32x16_bf16 v[80:95], v[104:107], v[140:143], v[80:95]
	v_mfma_f32_32x32x16_bf16 v[64:79], v[108:111], v[136:139], v[64:79]
	v_mfma_f32_32x32x16_bf16 v[80:95], v[156:159], v[136:139], v[80:95]
	v_mfma_f32_32x32x16_bf16 v[64:79], v[152:155], v[132:135], v[64:79]
	v_mfma_f32_32x32x16_bf16 v[80:95], v[178:181], v[132:135], v[80:95]
	v_mfma_f32_32x32x16_bf16 v[64:79], v[148:151], v[128:131], v[64:79]
	s_waitcnt lgkmcnt(0)
	v_mfma_f32_32x32x16_bf16 v[80:95], v[182:185], v[128:131], v[80:95]
